# XCD-leader workgroups also keep four generation-word polls in flight at each barrier
# baseline (speedup 1.0000x reference)
; __device__ __forceinline__ unsigned xb_ld(unsigned* p)              { return __hip_atomic_load(p, __ATOMIC_RELAXED, __HIP_MEMORY_SCOPE_AGENT); }
; __device__ __forceinline__ unsigned xb_add(unsigned* p, unsigned v) { return __hip_atomic_fetch_add(p, v, __ATOMIC_RELAXED, __HIP_MEMORY_SCOPE_AGENT); }
; #define XB_SPIN(cond, bar) do { unsigned _sp = 0; while (cond) { __builtin_amdgcn_s_sleep(1); \
;     if ((++_sp & 255u) == 0u) { if (xb_ld(&(bar)[XB_TMO])) break; if (_sp > XB_SPIN_CAP) { atomicAdd(&(bar)[XB_TMO], 1u); break; } } } } while (0)
; __device__ __forceinline__ void xcd_barrier(const XcdBarrier& b) {
;     ...
;             const unsigned og = xb_add(&bar[XB_TOP], 1u);
;             const unsigned tg = og / nx;
;             if (og + 1u == (tg + 1u) * nx) xb_add(&bar[XB_TOPGEN], 1u);
;             else XB_SPIN(xb_ld(&bar[XB_TOPGEN]) == tg, bar);
.LBB0_146:
	s_or_b64 exec, exec, s[8:9]
	v_cvt_f32_u32_e32 v3, v0
	s_waitcnt vmcnt(0)
	v_readfirstlane_b32 s6, v2
	s_add_u32 s8, s28, 0x3500
	s_addc_u32 s9, s29, 0
	v_rcp_iflag_f32_e32 v3, v3
	v_add_u32_e32 v1, s6, v1
	v_add_u32_e32 v4, 1, v1
	s_mov_b64 s[10:11], -1
	v_mul_f32_e32 v2, 0x4f7ffffe, v3
	v_cvt_u32_f32_e32 v2, v2
	v_sub_u32_e32 v3, 0, v0
	v_mul_lo_u32 v3, v3, v2
	v_mul_hi_u32 v3, v2, v3
	v_add_u32_e32 v2, v2, v3
	v_mul_hi_u32 v2, v1, v2
	v_mul_lo_u32 v3, v2, v0
	v_sub_u32_e32 v1, v1, v3
	v_add_u32_e32 v5, 1, v2
	v_cmp_ge_u32_e32 vcc, v1, v0
	v_sub_u32_e32 v3, v1, v0
	s_nop 0
	v_cndmask_b32_e32 v2, v2, v5, vcc
	v_cndmask_b32_e32 v1, v1, v3, vcc
	v_add_u32_e32 v3, 1, v2
	v_cmp_ge_u32_e32 vcc, v1, v0
	s_nop 1
	v_cndmask_b32_e32 v2, v2, v3, vcc
	v_mul_lo_u32 v1, v0, v2
	v_add_u32_e32 v0, v1, v0
	v_cmp_ne_u32_e32 vcc, v4, v0
	v_mov_b64_e32 v[0:1], s[8:9]
	s_and_saveexec_b64 s[6:7], vcc
	s_cbranch_execz .LBB0_158
	v_mov_b32_e32 v0, 0
	global_load_dword v1, v0, s[8:9] sc1
	s_mov_b64 s[14:15], 0
	s_waitcnt vmcnt(0)
	v_cmp_eq_u32_e32 vcc, v1, v2
	s_and_saveexec_b64 s[12:13], vcc
	s_cbranch_execz .LBB0_157
	s_add_u32 s10, s28, 0x200
	s_addc_u32 s11, s29, 0
	s_mov_b64 s[14:15], exec
	s_mov_b64 s[16:17], 0
	s_mov_b32 s25, 0
	global_load_dword v1, v0, s[8:9] sc1
	s_sleep 3
	global_load_dword v3, v0, s[8:9] sc1
	s_sleep 3
	global_load_dword v4, v0, s[8:9] sc1
	s_sleep 3
	global_load_dword v5, v0, s[8:9] sc1
.Lpoll_ldr_loop_0:
	s_waitcnt vmcnt(3)
	v_cmp_ne_u32_e32 vcc, v1, v2
	s_cbranch_vccnz .Lpoll_ldr_done_0
	global_load_dword v1, v0, s[8:9] sc1
	s_sleep 3
	s_waitcnt vmcnt(3)
	v_cmp_ne_u32_e32 vcc, v3, v2
	s_cbranch_vccnz .Lpoll_ldr_done_0
	global_load_dword v3, v0, s[8:9] sc1
	s_sleep 3
	s_waitcnt vmcnt(3)
	v_cmp_ne_u32_e32 vcc, v4, v2
	s_cbranch_vccnz .Lpoll_ldr_done_0
	global_load_dword v4, v0, s[8:9] sc1
	s_sleep 3
	s_waitcnt vmcnt(3)
	v_cmp_ne_u32_e32 vcc, v5, v2
	s_cbranch_vccnz .Lpoll_ldr_done_0
	global_load_dword v5, v0, s[8:9] sc1
	s_sleep 3
	s_add_i32 s25, s25, 1
	s_cmp_lt_u32 s25, 0x100000
	s_cbranch_scc1 .Lpoll_ldr_loop_0
	s_mov_b64 s[16:17], -1
.Lpoll_ldr_done_0:
	s_waitcnt vmcnt(0)
.LBB0_156:
	s_or_b64 exec, exec, s[14:15]
	s_and_b64 s[14:15], s[16:17], exec

; __device__ __forceinline__ unsigned xb_ld(unsigned* p)              { return __hip_atomic_load(p, __ATOMIC_RELAXED, __HIP_MEMORY_SCOPE_AGENT); }
; #define XB_SPIN(cond, bar) do { unsigned _sp = 0; while (cond) { __builtin_amdgcn_s_sleep(1); \
;     if ((++_sp & 255u) == 0u) { if (xb_ld(&(bar)[XB_TMO])) break; if (_sp > XB_SPIN_CAP) { atomicAdd(&(bar)[XB_TMO], 1u); break; } } } } while (0)
; __device__ __forceinline__ void xcd_barrier(const XcdBarrier& b) {
;     ...
;             else XB_SPIN(xb_ld(&bar[XB_TOPGEN]) == tg, bar);
.Lpoll_ldr_done_1:
	s_waitcnt vmcnt(0)
.LBB0_271:
	s_or_b64 exec, exec, s[14:15]
	s_and_b64 s[14:15], s[16:17], exec

; __device__ __forceinline__ unsigned xb_ld(unsigned* p)              { return __hip_atomic_load(p, __ATOMIC_RELAXED, __HIP_MEMORY_SCOPE_AGENT); }
; __device__ __forceinline__ unsigned xb_add(unsigned* p, unsigned v) { return __hip_atomic_fetch_add(p, v, __ATOMIC_RELAXED, __HIP_MEMORY_SCOPE_AGENT); }
; #define XB_SPIN(cond, bar) do { unsigned _sp = 0; while (cond) { __builtin_amdgcn_s_sleep(1); \
;     if ((++_sp & 255u) == 0u) { if (xb_ld(&(bar)[XB_TMO])) break; if (_sp > XB_SPIN_CAP) { atomicAdd(&(bar)[XB_TMO], 1u); break; } } } } while (0)
; __device__ __forceinline__ void xcd_barrier(const XcdBarrier& b) {
;     ...
;             const unsigned og = xb_add(&bar[XB_TOP], 1u);
;             const unsigned tg = og / nx;
;             if (og + 1u == (tg + 1u) * nx) xb_add(&bar[XB_TOPGEN], 1u);
;             else XB_SPIN(xb_ld(&bar[XB_TOPGEN]) == tg, bar);
.LBB0_354:
	s_or_b64 exec, exec, s[8:9]
	v_cvt_f32_u32_e32 v3, v0
	s_waitcnt vmcnt(0)
	v_readfirstlane_b32 s6, v2
	s_add_u32 s8, s28, 0x3500
	s_addc_u32 s9, s29, 0
	v_rcp_iflag_f32_e32 v3, v3
	v_add_u32_e32 v1, s6, v1
	v_add_u32_e32 v4, 1, v1
	s_mov_b64 s[10:11], -1
	v_mul_f32_e32 v2, 0x4f7ffffe, v3
	v_cvt_u32_f32_e32 v2, v2
	v_sub_u32_e32 v3, 0, v0
	v_mul_lo_u32 v3, v3, v2
	v_mul_hi_u32 v3, v2, v3
	v_add_u32_e32 v2, v2, v3
	v_mul_hi_u32 v2, v1, v2
	v_mul_lo_u32 v3, v2, v0
	v_sub_u32_e32 v1, v1, v3
	v_add_u32_e32 v5, 1, v2
	v_cmp_ge_u32_e32 vcc, v1, v0
	v_sub_u32_e32 v3, v1, v0
	s_nop 0
	v_cndmask_b32_e32 v2, v2, v5, vcc
	v_cndmask_b32_e32 v1, v1, v3, vcc
	v_add_u32_e32 v3, 1, v2
	v_cmp_ge_u32_e32 vcc, v1, v0
	s_nop 1
	v_cndmask_b32_e32 v2, v2, v3, vcc
	v_mul_lo_u32 v1, v0, v2
	v_add_u32_e32 v0, v1, v0
	v_cmp_ne_u32_e32 vcc, v4, v0
	v_mov_b64_e32 v[0:1], s[8:9]
	s_and_saveexec_b64 s[6:7], vcc
	s_cbranch_execz .LBB0_366
	v_mov_b32_e32 v0, 0
	global_load_dword v1, v0, s[8:9] sc1
	s_mov_b64 s[14:15], 0
	s_waitcnt vmcnt(0)
	v_cmp_eq_u32_e32 vcc, v1, v2
	s_and_saveexec_b64 s[12:13], vcc
	s_cbranch_execz .LBB0_365
	s_add_u32 s10, s28, 0x200
	s_addc_u32 s11, s29, 0
	s_mov_b64 s[14:15], exec
	s_mov_b64 s[16:17], 0
	s_mov_b32 s24, 0
	global_load_dword v1, v0, s[8:9] sc1
	s_sleep 3
	global_load_dword v3, v0, s[8:9] sc1
	s_sleep 3
	global_load_dword v4, v0, s[8:9] sc1
	s_sleep 3
	global_load_dword v5, v0, s[8:9] sc1
.Lpoll_ldr_loop_2:
	s_waitcnt vmcnt(3)
	v_cmp_ne_u32_e32 vcc, v1, v2
	s_cbranch_vccnz .Lpoll_ldr_done_2
	global_load_dword v1, v0, s[8:9] sc1
	s_sleep 3
	s_waitcnt vmcnt(3)
	v_cmp_ne_u32_e32 vcc, v3, v2
	s_cbranch_vccnz .Lpoll_ldr_done_2
	global_load_dword v3, v0, s[8:9] sc1
	s_sleep 3
	s_waitcnt vmcnt(3)
	v_cmp_ne_u32_e32 vcc, v4, v2
	s_cbranch_vccnz .Lpoll_ldr_done_2
	global_load_dword v4, v0, s[8:9] sc1
	s_sleep 3
	s_waitcnt vmcnt(3)
	v_cmp_ne_u32_e32 vcc, v5, v2
	s_cbranch_vccnz .Lpoll_ldr_done_2
	global_load_dword v5, v0, s[8:9] sc1
	s_sleep 3
	s_add_i32 s24, s24, 1
	s_cmp_lt_u32 s24, 0x100000
	s_cbranch_scc1 .Lpoll_ldr_loop_2
	s_mov_b64 s[16:17], -1
.Lpoll_ldr_done_2:
	s_waitcnt vmcnt(0)
.LBB0_364:
	s_or_b64 exec, exec, s[14:15]
	s_and_b64 s[14:15], s[16:17], exec

; __device__ __forceinline__ unsigned xb_ld(unsigned* p)              { return __hip_atomic_load(p, __ATOMIC_RELAXED, __HIP_MEMORY_SCOPE_AGENT); }
; #define XB_SPIN(cond, bar) do { unsigned _sp = 0; while (cond) { __builtin_amdgcn_s_sleep(1); \
;     if ((++_sp & 255u) == 0u) { if (xb_ld(&(bar)[XB_TMO])) break; if (_sp > XB_SPIN_CAP) { atomicAdd(&(bar)[XB_TMO], 1u); break; } } } } while (0)
; __device__ __forceinline__ void xcd_barrier(const XcdBarrier& b) {
;     ...
;             else XB_SPIN(xb_ld(&bar[XB_TOPGEN]) == tg, bar);
.Lpoll_ldr_done_3:
	s_waitcnt vmcnt(0)
.LBB0_443:
	s_or_b64 exec, exec, s[14:15]
	s_and_b64 s[14:15], s[16:17], exec

; __device__ __forceinline__ unsigned xb_ld(unsigned* p)              { return __hip_atomic_load(p, __ATOMIC_RELAXED, __HIP_MEMORY_SCOPE_AGENT); }
; #define XB_SPIN(cond, bar) do { unsigned _sp = 0; while (cond) { __builtin_amdgcn_s_sleep(1); \
;     if ((++_sp & 255u) == 0u) { if (xb_ld(&(bar)[XB_TMO])) break; if (_sp > XB_SPIN_CAP) { atomicAdd(&(bar)[XB_TMO], 1u); break; } } } } while (0)
; __device__ __forceinline__ void xcd_barrier(const XcdBarrier& b) {
;     ...
;             else XB_SPIN(xb_ld(&bar[XB_TOPGEN]) == tg, bar);
.Lpoll_ldr_done_4:
	s_waitcnt vmcnt(0)
.LBB0_496:
	s_or_b64 exec, exec, s[14:15]
	s_and_b64 s[14:15], s[16:17], exec

; __device__ __forceinline__ unsigned xb_ld(unsigned* p)              { return __hip_atomic_load(p, __ATOMIC_RELAXED, __HIP_MEMORY_SCOPE_AGENT); }
; #define XB_SPIN(cond, bar) do { unsigned _sp = 0; while (cond) { __builtin_amdgcn_s_sleep(1); \
;     if ((++_sp & 255u) == 0u) { if (xb_ld(&(bar)[XB_TMO])) break; if (_sp > XB_SPIN_CAP) { atomicAdd(&(bar)[XB_TMO], 1u); break; } } } } while (0)
; __device__ __forceinline__ void xcd_barrier(const XcdBarrier& b) {
;     ...
;             else XB_SPIN(xb_ld(&bar[XB_TOPGEN]) == tg, bar);
.Lpoll_ldr_done_5:
	s_waitcnt vmcnt(0)
.LBB0_567:
	s_or_b64 exec, exec, s[14:15]
	s_and_b64 s[14:15], s[16:17], exec

; __device__ __forceinline__ unsigned xb_ld(unsigned* p)              { return __hip_atomic_load(p, __ATOMIC_RELAXED, __HIP_MEMORY_SCOPE_AGENT); }
; #define XB_SPIN(cond, bar) do { unsigned _sp = 0; while (cond) { __builtin_amdgcn_s_sleep(1); \
;     if ((++_sp & 255u) == 0u) { if (xb_ld(&(bar)[XB_TMO])) break; if (_sp > XB_SPIN_CAP) { atomicAdd(&(bar)[XB_TMO], 1u); break; } } } } while (0)
; __device__ __forceinline__ void xcd_barrier(const XcdBarrier& b) {
;     ...
;             else XB_SPIN(xb_ld(&bar[XB_TOPGEN]) == tg, bar);
.Lpoll_ldr_done_6:
	s_waitcnt vmcnt(0)
.LBB0_646:
	s_or_b64 exec, exec, s[14:15]
	s_and_b64 s[14:15], s[16:17], exec

; __device__ __forceinline__ unsigned xb_ld(unsigned* p)              { return __hip_atomic_load(p, __ATOMIC_RELAXED, __HIP_MEMORY_SCOPE_AGENT); }
; #define XB_SPIN(cond, bar) do { unsigned _sp = 0; while (cond) { __builtin_amdgcn_s_sleep(1); \
;     if ((++_sp & 255u) == 0u) { if (xb_ld(&(bar)[XB_TMO])) break; if (_sp > XB_SPIN_CAP) { atomicAdd(&(bar)[XB_TMO], 1u); break; } } } } while (0)
; __device__ __forceinline__ void xcd_barrier(const XcdBarrier& b) {
;     ...
;             else XB_SPIN(xb_ld(&bar[XB_TOPGEN]) == tg, bar);
.Lpoll_ldr_done_7:
	s_waitcnt vmcnt(0)
.LBB0_739:
	s_or_b64 exec, exec, s[14:15]
	s_and_b64 s[14:15], s[16:17], exec

; __device__ __forceinline__ unsigned xb_ld(unsigned* p)              { return __hip_atomic_load(p, __ATOMIC_RELAXED, __HIP_MEMORY_SCOPE_AGENT); }
; #define XB_SPIN(cond, bar) do { unsigned _sp = 0; while (cond) { __builtin_amdgcn_s_sleep(1); \
;     if ((++_sp & 255u) == 0u) { if (xb_ld(&(bar)[XB_TMO])) break; if (_sp > XB_SPIN_CAP) { atomicAdd(&(bar)[XB_TMO], 1u); break; } } } } while (0)
; __device__ __forceinline__ void xcd_barrier(const XcdBarrier& b) {
;     ...
;             else XB_SPIN(xb_ld(&bar[XB_TOPGEN]) == tg, bar);
.Lpoll_ldr_done_8:
	s_waitcnt vmcnt(0)
.LBB0_849:
	s_or_b64 exec, exec, s[14:15]
	s_and_b64 s[14:15], s[16:17], exec

; __device__ __forceinline__ unsigned xb_ld(unsigned* p)              { return __hip_atomic_load(p, __ATOMIC_RELAXED, __HIP_MEMORY_SCOPE_AGENT); }
; #define XB_SPIN(cond, bar) do { unsigned _sp = 0; while (cond) { __builtin_amdgcn_s_sleep(1); \
;     if ((++_sp & 255u) == 0u) { if (xb_ld(&(bar)[XB_TMO])) break; if (_sp > XB_SPIN_CAP) { atomicAdd(&(bar)[XB_TMO], 1u); break; } } } } while (0)
; __device__ __forceinline__ void xcd_barrier(const XcdBarrier& b) {
;     ...
;             else XB_SPIN(xb_ld(&bar[XB_TOPGEN]) == tg, bar);
.Lpoll_ldr_done_9:
	s_waitcnt vmcnt(0)
.LBB0_1004:
	s_or_b64 exec, exec, s[14:15]
	s_and_b64 s[14:15], s[16:17], exec

; __device__ __forceinline__ unsigned xb_ld(unsigned* p)              { return __hip_atomic_load(p, __ATOMIC_RELAXED, __HIP_MEMORY_SCOPE_AGENT); }
; #define XB_SPIN(cond, bar) do { unsigned _sp = 0; while (cond) { __builtin_amdgcn_s_sleep(1); \
;     if ((++_sp & 255u) == 0u) { if (xb_ld(&(bar)[XB_TMO])) break; if (_sp > XB_SPIN_CAP) { atomicAdd(&(bar)[XB_TMO], 1u); break; } } } } while (0)
; __device__ __forceinline__ void xcd_barrier(const XcdBarrier& b) {
;     ...
;             else XB_SPIN(xb_ld(&bar[XB_TOPGEN]) == tg, bar);
.Lpoll_ldr_done_10:
	s_waitcnt vmcnt(0)
.LBB0_1083:
	s_or_b64 exec, exec, s[14:15]
	s_and_b64 s[14:15], s[16:17], exec

; __device__ __forceinline__ unsigned xb_ld(unsigned* p)              { return __hip_atomic_load(p, __ATOMIC_RELAXED, __HIP_MEMORY_SCOPE_AGENT); }
; #define XB_SPIN(cond, bar) do { unsigned _sp = 0; while (cond) { __builtin_amdgcn_s_sleep(1); \
;     if ((++_sp & 255u) == 0u) { if (xb_ld(&(bar)[XB_TMO])) break; if (_sp > XB_SPIN_CAP) { atomicAdd(&(bar)[XB_TMO], 1u); break; } } } } while (0)
; __device__ __forceinline__ void xcd_barrier(const XcdBarrier& b) {
;     ...
;             else XB_SPIN(xb_ld(&bar[XB_TOPGEN]) == tg, bar);
.Lpoll_ldr_done_11:
	s_waitcnt vmcnt(0)
.LBB0_1136:
	s_or_b64 exec, exec, s[14:15]
	s_and_b64 s[14:15], s[16:17], exec

; __device__ __forceinline__ unsigned xb_ld(unsigned* p)              { return __hip_atomic_load(p, __ATOMIC_RELAXED, __HIP_MEMORY_SCOPE_AGENT); }
; #define XB_SPIN(cond, bar) do { unsigned _sp = 0; while (cond) { __builtin_amdgcn_s_sleep(1); \
;     if ((++_sp & 255u) == 0u) { if (xb_ld(&(bar)[XB_TMO])) break; if (_sp > XB_SPIN_CAP) { atomicAdd(&(bar)[XB_TMO], 1u); break; } } } } while (0)
; __device__ __forceinline__ void xcd_barrier(const XcdBarrier& b) {
;     ...
;             else XB_SPIN(xb_ld(&bar[XB_TOPGEN]) == tg, bar);
.Lpoll_ldr_done_12:
	s_waitcnt vmcnt(0)
.LBB0_1207:
	s_or_b64 exec, exec, s[14:15]
	s_and_b64 s[14:15], s[16:17], exec

; __device__ __forceinline__ unsigned xb_ld(unsigned* p)              { return __hip_atomic_load(p, __ATOMIC_RELAXED, __HIP_MEMORY_SCOPE_AGENT); }
; #define XB_SPIN(cond, bar) do { unsigned _sp = 0; while (cond) { __builtin_amdgcn_s_sleep(1); \
;     if ((++_sp & 255u) == 0u) { if (xb_ld(&(bar)[XB_TMO])) break; if (_sp > XB_SPIN_CAP) { atomicAdd(&(bar)[XB_TMO], 1u); break; } } } } while (0)
; __device__ __forceinline__ void xcd_barrier(const XcdBarrier& b) {
;     ...
;             else XB_SPIN(xb_ld(&bar[XB_TOPGEN]) == tg, bar);
.Lpoll_ldr_done_13:
	s_waitcnt vmcnt(0)
.LBB0_1286:
	s_or_b64 exec, exec, s[14:15]
	s_and_b64 s[14:15], s[16:17], exec
